# stack2 + scan2 counted vmcnt and hoisted fragment reads + scan1: next-chunk parameter rows prefetched with the operand prefetch, v83 copy replaced by a second load (no wait right after issue)
# baseline (speedup 1.0000x reference)
; __device__ __forceinline__ void lds_barrier() { asm volatile("s_waitcnt lgkmcnt(0)" ::: "memory"); __builtin_amdgcn_s_barrier(); asm volatile("" ::: "memory"); }
; __device__ __forceinline__ void phase_scan1(Frame& F, int l) {
;     ...
;     LORA_LOAD((int)blockIdx.x); SCAN1_LOAD((int)blockIdx.x);
;     lds_barrier();
;     LORA_COMPUTE((int)blockIdx.x);
;     lds_barrier();
.LBB0_508:
	s_add_u32 s25, s6, 0x3d5a0000
	s_addc_u32 s26, s7, 0
	v_readlane_b32 s22, v255, 35
	s_add_u32 s22, s25, s22
	v_readlane_b32 s23, v255, 34
	s_addc_u32 s23, s26, s23
	s_add_u32 s22, s22, s27
	s_addc_u32 s23, s23, 0
	s_add_u32 s22, s22, 0x1000
	s_addc_u32 s23, s23, 0
	v_lshl_add_u64 v[42:43], s[14:15], 0, v[0:1]
	global_load_ushort v45, v[42:43], off
	s_nop 0
	global_load_ushort v42, v[42:43], off offset:2048
	v_lshl_add_u64 v[46:47], s[22:23], 0, v[0:1]
	v_add_u32_e32 v43, 0x5200, v0
	v_add_u32_e32 v44, 0x1800, v0
	global_load_ushort v47, v[46:47], off
	s_nop 0
	global_load_ushort v48, v43, s[14:15]
	s_nop 0
	global_load_ushort v43, v43, s[14:15] offset:2048
	v_add_u32_e32 v46, 0x3000, v0
	global_load_ushort v49, v44, s[22:23]
	v_add_u32_e32 v44, 0xa400, v0
	global_load_ushort v51, v44, s[14:15]
	s_nop 0
	global_load_ushort v44, v44, s[14:15] offset:2048
	v_add_u32_e32 v50, 0x4800, v0
	global_load_ushort v52, v46, s[22:23]
	v_add_u32_e32 v46, 0xf600, v0
	global_load_ushort v53, v46, s[14:15]
	s_nop 0
	global_load_ushort v46, v46, s[14:15] offset:2048
	v_add_u32_e32 v55, 0x6000, v0
	global_load_ushort v54, v50, s[22:23]
	v_add_u32_e32 v50, 0x14800, v0
	global_load_ushort v56, v50, s[14:15]
	s_nop 0
	global_load_ushort v50, v50, s[14:15] offset:2048
	v_add_u32_e32 v58, 0x7800, v0
	global_load_ushort v57, v55, s[22:23]
	v_add_u32_e32 v55, 0x19a00, v0
	global_load_ushort v60, v55, s[14:15]
	s_nop 0
	global_load_ushort v55, v55, s[14:15] offset:2048
	v_add_u32_e32 v59, 0x9000, v0
	global_load_ushort v61, v58, s[22:23]
	v_add_u32_e32 v58, 0x1ec00, v0
	global_load_ushort v62, v58, s[14:15]
	s_nop 0
	global_load_ushort v58, v58, s[14:15] offset:2048
	v_mov_b32_e32 v66, v85
	global_load_ushort v63, v59, s[22:23]
	v_add_u32_e32 v59, 0x23e00, v0
	v_add_u32_e32 v0, 0xa800, v0
	global_load_ushort v64, v59, s[14:15]
	s_nop 0
	global_load_ushort v59, v59, s[14:15] offset:2048
	v_readlane_b32 s14, v255, 9
	global_load_ushort v0, v0, s[22:23]
	s_waitcnt lgkmcnt(0)
	s_barrier
	v_lshl_add_u32 v99, s14, 2, v65
	v_and_b32_e32 v65, -16, v66
	v_and_or_b32 v66, v66, 15, s97
	v_readlane_b32 s14, v254, 30
	v_cndmask_b32_e64 v100, v91, v96, s[4:5]
	v_mul_u32_u24_e32 v66, 0x110, v66
	v_add3_u32 v75, v99, s14, v65
	v_add3_u32 v65, v100, v66, v65
	s_waitcnt vmcnt(31)
	v_mfma_f32_16x16x32_bf16 v[66:69], v[10:13], v[2:5], 0
	ds_read_b128 v[70:73], v75
	v_mov_b32_e32 v195, v194
	v_readlane_b32 s14, v254, 31
	s_waitcnt vmcnt(30)
	v_mfma_f32_16x16x32_bf16 v[66:69], v[14:17], v[6:9], v[66:69]
	v_readlane_b32 s15, v254, 32
	s_andn2_b64 vcc, exec, s[14:15]
	s_waitcnt lgkmcnt(0)
	s_nop 4
	v_add_f32_e32 v66, v66, v70
	v_add_f32_e32 v67, v67, v71
	v_add_f32_e32 v68, v68, v72
	v_add_f32_e32 v69, v69, v73
	v_mul_f32_e32 v66, 0xbfb8aa3b, v66
	v_mul_f32_e32 v67, 0xbfb8aa3b, v67
	v_mul_f32_e32 v68, 0xbfb8aa3b, v68
	v_mul_f32_e32 v69, 0xbfb8aa3b, v69
	v_exp_f32_e32 v66, v66
	v_exp_f32_e32 v67, v67
	v_exp_f32_e32 v68, v68
	v_exp_f32_e32 v69, v69
	v_add_f32_e32 v66, 1.0, v66
	v_add_f32_e32 v67, 1.0, v67
	v_add_f32_e32 v68, 1.0, v68
	v_add_f32_e32 v69, 1.0, v69
	v_rcp_f32_e32 v66, v66
	v_rcp_f32_e32 v67, v67
	v_rcp_f32_e32 v68, v68
	v_rcp_f32_e32 v69, v69
	v_pk_mul_f32 v[66:67], v[196:197], v[66:67]
	v_pk_mul_f32 v[68:69], v[194:195], v[68:69]
	ds_write_b128 v65, v[66:69]
	s_waitcnt vmcnt(29)
	v_mfma_f32_16x16x32_bf16 v[66:69], v[18:21], v[2:5], 0
	ds_read_b128 v[70:73], v75 offset:64
	s_waitcnt vmcnt(28)
	v_mfma_f32_16x16x32_bf16 v[66:69], v[22:25], v[6:9], v[66:69]
	s_waitcnt lgkmcnt(0)
	s_nop 6
	v_add_f32_e32 v66, v66, v70
	v_add_f32_e32 v67, v67, v71
	v_add_f32_e32 v68, v68, v72
	v_add_f32_e32 v69, v69, v73
	v_mul_f32_e32 v66, 0xbfb8aa3b, v66
	v_mul_f32_e32 v67, 0xbfb8aa3b, v67
	v_mul_f32_e32 v68, 0xbfb8aa3b, v68
	v_mul_f32_e32 v69, 0xbfb8aa3b, v69
	v_exp_f32_e32 v66, v66
	v_exp_f32_e32 v67, v67
	v_exp_f32_e32 v68, v68
	v_exp_f32_e32 v69, v69
	v_add_f32_e32 v66, 1.0, v66
	v_add_f32_e32 v67, 1.0, v67
	v_add_f32_e32 v68, 1.0, v68
	v_add_f32_e32 v69, 1.0, v69
	v_rcp_f32_e32 v66, v66
	v_rcp_f32_e32 v67, v67
	v_rcp_f32_e32 v68, v68
	v_rcp_f32_e32 v69, v69
	v_pk_mul_f32 v[66:67], v[196:197], v[66:67]
	v_pk_mul_f32 v[68:69], v[194:195], v[68:69]
	ds_write_b128 v65, v[66:69] offset:64
	s_waitcnt vmcnt(27)
	v_mfma_f32_16x16x32_bf16 v[66:69], v[26:29], v[2:5], 0
	ds_read_b128 v[70:73], v75 offset:128
	s_waitcnt vmcnt(26)
	v_mfma_f32_16x16x32_bf16 v[66:69], v[30:33], v[6:9], v[66:69]
	s_waitcnt lgkmcnt(0)
	s_nop 6
	v_add_f32_e32 v66, v66, v70
	v_add_f32_e32 v67, v67, v71
	v_add_f32_e32 v68, v68, v72
	v_add_f32_e32 v69, v69, v73
	v_mul_f32_e32 v66, 0xbfb8aa3b, v66
	v_mul_f32_e32 v67, 0xbfb8aa3b, v67
	v_mul_f32_e32 v68, 0xbfb8aa3b, v68
	v_mul_f32_e32 v69, 0xbfb8aa3b, v69
	v_exp_f32_e32 v66, v66
	v_exp_f32_e32 v67, v67
	v_exp_f32_e32 v68, v68
	v_exp_f32_e32 v69, v69
	v_add_f32_e32 v66, 1.0, v66
	v_add_f32_e32 v67, 1.0, v67
	v_add_f32_e32 v68, 1.0, v68
	v_add_f32_e32 v69, 1.0, v69
	v_rcp_f32_e32 v66, v66
	v_rcp_f32_e32 v67, v67
	v_rcp_f32_e32 v68, v68
	v_rcp_f32_e32 v69, v69
	v_pk_mul_f32 v[66:67], v[196:197], v[66:67]
	v_pk_mul_f32 v[68:69], v[194:195], v[68:69]
	ds_write_b128 v65, v[66:69] offset:128
	s_waitcnt vmcnt(25)
	v_mfma_f32_16x16x32_bf16 v[66:69], v[34:37], v[2:5], 0
	ds_read_b128 v[70:73], v75 offset:192
	s_waitcnt vmcnt(24)
	v_mfma_f32_16x16x32_bf16 v[66:69], v[38:41], v[6:9], v[66:69]
	s_waitcnt lgkmcnt(0)
	s_nop 6
	v_add_f32_e32 v66, v66, v70
	v_add_f32_e32 v67, v67, v71
	v_add_f32_e32 v68, v68, v72
	v_add_f32_e32 v69, v69, v73
	v_mul_f32_e32 v66, 0xbfb8aa3b, v66
	v_mul_f32_e32 v67, 0xbfb8aa3b, v67
	v_mul_f32_e32 v68, 0xbfb8aa3b, v68
	v_mul_f32_e32 v69, 0xbfb8aa3b, v69
	v_exp_f32_e32 v66, v66
	v_exp_f32_e32 v67, v67
	v_exp_f32_e32 v68, v68
	v_exp_f32_e32 v69, v69
	v_add_f32_e32 v66, 1.0, v66
	v_add_f32_e32 v67, 1.0, v67
	v_add_f32_e32 v68, 1.0, v68
	v_add_f32_e32 v69, 1.0, v69
	v_rcp_f32_e32 v66, v66
	v_rcp_f32_e32 v67, v67
	v_rcp_f32_e32 v68, v68
	v_rcp_f32_e32 v69, v69
	v_pk_mul_f32 v[66:67], v[196:197], v[66:67]
	v_pk_mul_f32 v[68:69], v[194:195], v[68:69]
	ds_write_b128 v65, v[66:69] offset:192
	s_waitcnt lgkmcnt(0)
	s_barrier
; __device__ __forceinline__ int launder_v(int v) { asm volatile("" : "+v"(v)); return v; }
; __device__ __forceinline__ void phase_scan1(Frame& F, int l) {
;     ...
;         int m0, h; chunk_coords(cidx, m0, h);
;         float khv[8], bhv[8], rv[8], kv[8], vv[8], av[8], lwv[8];
; #pragma unroll
;         for (int i = 0; i < 8; ++i) { rv[i] = __builtin_bit_cast(float, rvw[i] << 16); kv[i] = __builtin_bit_cast(float, kvw[i] << 16); vv[i] = __builtin_bit_cast(float, vvw[i] << 16); }
;         float rprev = __builtin_bit_cast(float, rpw << 16), kprev = __builtin_bit_cast(float, kpw << 16);
;         { const int lane = launder_v(lane0);
; #pragma unroll
;           for (int i = 0; i < 8; ++i) { lwv[i] = STW[(8 * w + i) * XP + lane]; av[i] = STA[(8 * w + i) * XP + lane]; } }
;         {   STAGE_LANE; const int col = h * 64 + lane;
;         const unsigned vo4 = (unsigned)lane * 4u; const float kkc = ldg_f32(k_k + h * 64, vo4), kac = ldg_f32(k_a + h * 64, vo4), rkc = ldg_f32(r_k + h * 64, vo4), mur = ldg_f32(mu_ + h * 64, vo4), muk = ldg_f32(mu_ + 1024 + h * 64, vo4); (void)col;
	s_cbranch_vccnz .LBB0_580
	s_lshl_b32 s14, s49, 1
	s_add_u32 s27, s1, s31
	s_addc_u32 s28, s13, 0
	s_add_u32 s29, s29, s31
	s_addc_u32 s30, s30, 0
	s_add_u32 s31, s6, 0x47fa0000
	s_addc_u32 s34, s7, 0
	v_add_u32_e32 v101, s14, v89
	v_add_u32_e32 v102, s14, v90
	v_add_u32_e32 v103, s14, v88
	s_add_u32 s14, s6, 0x4c3a0000
	s_addc_u32 s15, s7, 0
	s_lshl_b64 s[20:21], s[20:21], 2
	s_add_u32 s35, s8, s20
	s_addc_u32 s36, s9, s21
	s_add_u32 s37, s10, s20
	s_addc_u32 s38, s11, s21
	s_add_u32 s39, s18, s20
	s_addc_u32 s48, s19, s21
	s_mul_i32 s8, s12, 0x3400
	s_mul_hi_i32 s1, s12, 0x3400
	s_add_u32 s52, s16, s8
	s_addc_u32 s53, s17, s1
	v_readlane_b32 s1, v254, 14
	s_add_u32 s61, s52, 0x1000
	s_addc_u32 s62, s53, 0
	v_lshl_add_u32 v104, s1, 2, v97
	v_readlane_b32 s1, v255, 40
	s_waitcnt vmcnt(22)
	v_and_b32_e32 v78, 0xffff, v42
	v_and_b32_e32 v109, 0xffff, v45
	v_add_u32_e32 v105, s1, v96
	v_add_u32_e32 v106, s1, v91
	s_lshl_b32 s1, s58, 1
	s_add_u32 s1, s6, s1
	s_addc_u32 s6, s7, 0
	s_add_u32 s64, s1, 0x43ba0000
	s_mul_i32 s1, s47, 0x900
	s_waitcnt vmcnt(21)
	v_and_b32_e32 v110, 0xffff, v47
	s_waitcnt vmcnt(20)
	v_and_b32_e32 v111, 0xffff, v48
	s_waitcnt vmcnt(18)
	v_and_b32_e32 v112, 0xffff, v49
	s_waitcnt vmcnt(17)
	v_and_b32_e32 v113, 0xffff, v51
	s_waitcnt vmcnt(15)
	v_and_b32_e32 v114, 0xffff, v52
	s_waitcnt vmcnt(14)
	v_and_b32_e32 v115, 0xffff, v53
	s_waitcnt vmcnt(12)
	v_and_b32_e32 v116, 0xffff, v54
	s_waitcnt vmcnt(11)
	v_and_b32_e32 v117, 0xffff, v56
	s_waitcnt vmcnt(9)
	v_and_b32_e32 v118, 0xffff, v57
	s_waitcnt vmcnt(8)
	v_and_b32_e32 v119, 0xffff, v60
	s_waitcnt vmcnt(6)
	v_and_b32_e32 v120, 0xffff, v61
	s_waitcnt vmcnt(5)
	v_and_b32_e32 v121, 0xffff, v62
	s_waitcnt vmcnt(3)
	v_and_b32_e32 v122, 0xffff, v63
	s_waitcnt vmcnt(2)
	v_and_b32_e32 v123, 0xffff, v64
	s_waitcnt vmcnt(0)
	v_and_b32_e32 v124, 0xffff, v0
	v_and_b32_e32 v81, 0xffff, v59
	v_and_b32_e32 v84, 0xffff, v58
	v_and_b32_e32 v79, 0xffff, v55
	v_and_b32_e32 v82, 0xffff, v50
	v_and_b32_e32 v77, 0xffff, v46
	v_and_b32_e32 v80, 0xffff, v44
	v_and_b32_e32 v75, 0xffff, v43
	v_add_u32_e32 v107, s59, v93
	s_addc_u32 s65, s6, 0
	v_mov_b32_e32 v83, v78
	v_add_u32_e32 v108, s1, v74
	s_lshr_b32 s98, s2, 6
	s_cmpk_gt_i32 s2, 0xfff
	s_cselect_b32 s98, s2, s98
	s_and_b32 s98, s98, 15
	s_lshl_b32 s98, s98, 8
	v_lshlrev_b32_e32 v203, 2, v85
	s_add_u32 s100, s35, s98
	s_addc_u32 s101, s36, 0
	global_load_dword v198, v203, s[100:101]
	s_add_u32 s100, s37, s98
	s_addc_u32 s101, s38, 0
	global_load_dword v199, v203, s[100:101]
	s_add_u32 s100, s39, s98
	s_addc_u32 s101, s48, 0
	global_load_dword v200, v203, s[100:101]
	s_add_u32 s100, s52, s98
	s_addc_u32 s101, s53, 0
	global_load_dword v201, v203, s[100:101]
	s_add_u32 s100, s61, s98
	s_addc_u32 s101, s62, 0
	global_load_dword v202, v203, s[100:101]
	s_waitcnt vmcnt(0)
	s_mov_b32 s72, s2
	s_branch .LBB0_511

; #define LAS __attribute__((address_space(3)))
; __device__ __forceinline__ int launder_v(int v) { asm volatile("" : "+v"(v)); return v; }
; __device__ __forceinline__ void phase_scan1(Frame& F, int l) {
;     ...
;         int m0, h; chunk_coords(cidx, m0, h);
;         float khv[8], bhv[8], rv[8], kv[8], vv[8], av[8], lwv[8];
; #pragma unroll
;         for (int i = 0; i < 8; ++i) { rv[i] = __builtin_bit_cast(float, rvw[i] << 16); kv[i] = __builtin_bit_cast(float, kvw[i] << 16); vv[i] = __builtin_bit_cast(float, vvw[i] << 16); }
;         float rprev = __builtin_bit_cast(float, rpw << 16), kprev = __builtin_bit_cast(float, kpw << 16);
;         { const int lane = launder_v(lane0);
; #pragma unroll
;           for (int i = 0; i < 8; ++i) { lwv[i] = STW[(8 * w + i) * XP + lane]; av[i] = STA[(8 * w + i) * XP + lane]; } }
;         {   STAGE_LANE; const int col = h * 64 + lane;
;         const unsigned vo4 = (unsigned)lane * 4u; const float kkc = ldg_f32(k_k + h * 64, vo4), kac = ldg_f32(k_a + h * 64, vo4), rkc = ldg_f32(r_k + h * 64, vo4), mur = ldg_f32(mu_ + h * 64, vo4), muk = ldg_f32(mu_ + 1024 + h * 64, vo4); (void)col;
; #pragma unroll
;         for (int i = 0; i < 8; ++i) { const float rc = rv[i], kc = kv[i]; rv[i] = rc + mur * (rprev - rc); kv[i] = kc + muk * (kprev - kc); rprev = rc; kprev = kc; }
;         float pre[8]; { float run = 0.f;
; #pragma unroll
;             for (int i = 0; i < 8; ++i) { run += lwv[i]; pre[i] = run; }
;             GT[w * 64 + lane] = run; }
;         float kkrv[8], kpv[8];
;         { LAS float* S1 = STW + 8 * w * XP + lane; LAS float* S2 = STA + 8 * w * XP + lane;
; #pragma unroll
;           for (int i = 0; i < 8; ++i) { kkrv[i] = kv[i] * kkc; kpv[i] = kv[i] * (1.0f + (av[i] - 1.0f) * kac); S1[i * XP] = kkrv[i] * kkrv[i]; S2[i * XP] = rv[i] * kpv[i] * rkc; } }
.LBB0_515:
	v_mov_b32_e32 v0, v85
	v_readlane_b32 s6, v255, 26
	v_lshlrev_b32_e32 v42, 2, v0
	v_add_u32_e32 v43, v105, v42
	v_add_u32_e32 v42, v106, v42
	v_add_lshl_u32 v0, v0, s6, 2
	ds_read_b32 v56, v42
	v_add_u32_e32 v42, v96, v0
	s_and_b32 s1, s1, 15
	ds_read_b32 v137, v43
	v_add_u32_e32 v0, v91, v0
	v_add_u32_e32 v43, 0x400, v42
	s_lshl_b32 s80, s1, 8
	ds_read2_b32 v[54:55], v42 offset1:68
	ds_read2_b32 v[52:53], v0 offset1:68
	ds_read2_b32 v[50:51], v42 offset0:136 offset1:204
	ds_read2_b32 v[48:49], v0 offset0:136 offset1:204
	ds_read2_b32 v[46:47], v43 offset0:16 offset1:84
	v_add_u32_e32 v43, 0x400, v0
	v_mov_b32_e32 v135, v85
	s_add_u32 s6, s35, s80
	ds_read2_b32 v[44:45], v43 offset0:16 offset1:84
	ds_read_b32 v129, v42 offset:1632
	ds_read_b32 v43, v0 offset:1632
	s_addc_u32 s7, s36, 0
	v_lshlrev_b32_e32 v70, 2, v135
	v_mov_b32_e32 v71, v198
	s_add_u32 s6, s37, s80
	s_addc_u32 s7, s38, 0
	v_mov_b32_e32 v0, v199
	s_add_u32 s6, s39, s80
	s_addc_u32 s7, s48, 0
	v_mov_b32_e32 v72, v200
	s_add_u32 s6, s52, s80
	s_addc_u32 s7, s53, 0
	v_mov_b32_e32 v68, v201
	s_add_u32 s6, s61, s80
	s_addc_u32 s7, s62, 0
	v_mov_b32_e32 v42, v202
	s_waitcnt lgkmcnt(8)
	v_add_f32_e32 v143, 0, v137
	v_lshlrev_b32_e32 v133, 16, v109
	v_lshlrev_b32_e32 v132, 16, v111
	v_lshlrev_b32_e32 v57, 16, v98
	s_waitcnt lgkmcnt(7)
	v_add_f32_e32 v142, v143, v54
	s_waitcnt vmcnt(30)
	v_lshlrev_b32_e32 v131, 16, v113
	s_waitcnt vmcnt(27)
	v_lshlrev_b32_e32 v130, 16, v115
	v_sub_f32_e32 v57, v57, v133
	v_sub_f32_e32 v69, v133, v132
	v_add_f32_e32 v141, v142, v55
	s_waitcnt vmcnt(24)
	v_lshlrev_b32_e32 v128, 16, v117
	s_waitcnt vmcnt(21)
	v_lshlrev_b32_e32 v127, 16, v119
	s_waitcnt lgkmcnt(5)
	v_add_f32_e32 v140, v141, v50
	v_lshlrev_b32_e32 v67, 16, v83
	v_lshlrev_b32_e32 v66, 16, v76
	v_lshlrev_b32_e32 v65, 16, v75
	v_lshlrev_b32_e32 v64, 16, v78
	s_waitcnt vmcnt(18)
	v_lshlrev_b32_e32 v126, 16, v121
	s_waitcnt vmcnt(15)
	v_lshlrev_b32_e32 v125, 16, v123
	v_add_f32_e32 v139, v140, v51
	s_waitcnt lgkmcnt(3)
	v_add_f32_e32 v138, v139, v46
	v_pk_add_f32 v[66:67], v[66:67], v[64:65] neg_lo:[0,1] neg_hi:[0,1]
	v_add_f32_e32 v136, v138, v47
	s_waitcnt lgkmcnt(1)
	v_add_f32_e32 v134, v136, v129
	v_add_u32_e32 v73, v105, v70
	v_lshlrev_b32_e32 v63, 16, v77
	v_lshlrev_b32_e32 v62, 16, v80
	v_add_u32_e32 v150, v106, v70
	v_lshlrev_b32_e32 v59, 16, v79
	v_lshlrev_b32_e32 v58, 16, v82
	v_lshlrev_b32_e32 v60, 16, v84
	s_waitcnt vmcnt(14)
	v_lshlrev_b32_e32 v61, 16, v81
	v_and_b32_e32 v170, 7, v135
	v_lshlrev_b32_e32 v151, 5, v170
	v_cmp_eq_u32_e32 vcc, 0, v170
	v_fmac_f32_e32 v133, v57, v68
	v_sub_f32_e32 v57, v132, v131
	v_fmac_f32_e32 v132, v69, v68
	v_sub_f32_e32 v69, v131, v130
	v_fmac_f32_e32 v131, v57, v68
	v_sub_f32_e32 v57, v130, v128
	v_fmac_f32_e32 v130, v69, v68
	v_sub_f32_e32 v69, v128, v127
	v_fmac_f32_e32 v128, v57, v68
	v_sub_f32_e32 v57, v127, v126
	v_fmac_f32_e32 v127, v69, v68
	v_sub_f32_e32 v69, v126, v125
	v_fmac_f32_e32 v126, v57, v68
	v_fmac_f32_e32 v125, v69, v68
	s_waitcnt lgkmcnt(0)
	v_pk_fma_f32 v[68:69], v[66:67], v[42:43], v[64:65] op_sel_hi:[1,0,1]
	v_add_u32_e32 v57, v104, v70
	v_mul_f32_e32 v145, v71, v68
	ds_write_b32 v57, v134 offset:4352
	v_mul_f32_e32 v57, v145, v145
	ds_write_b32 v73, v57
	v_mov_b32_e32 v57, v52
	v_pk_add_f32 v[66:67], v[56:57], -1.0 op_sel_hi:[1,0]
	v_pk_mov_b32 v[64:65], v[64:65], v[62:63] op_sel:[1,0]
	v_pk_fma_f32 v[66:67], v[66:67], v[0:1], 1.0 op_sel_hi:[1,0,0]
	v_mul_f32_e32 v149, v71, v69
	v_pk_mul_f32 v[66:67], v[66:67], v[68:69]
	v_pk_add_f32 v[64:65], v[64:65], v[62:63] neg_lo:[0,1] neg_hi:[0,1]
	v_mul_f32_e32 v57, v133, v66
	v_mul_f32_e32 v57, v72, v57
	ds_write_b32 v150, v57
	v_mul_f32_e32 v57, v149, v149
	v_pk_fma_f32 v[68:69], v[64:65], v[42:43], v[62:63] op_sel_hi:[1,0,1]
	v_mov_b32_e32 v64, v53
	v_mov_b32_e32 v65, v48
	ds_write_b32 v73, v57 offset:272
	v_mul_f32_e32 v57, v132, v67
	v_pk_add_f32 v[64:65], v[64:65], -1.0 op_sel_hi:[1,0]
	v_mul_f32_e32 v57, v72, v57
	v_mul_f32_e32 v148, v71, v68
	v_pk_fma_f32 v[64:65], v[64:65], v[0:1], 1.0 op_sel_hi:[1,0,0]
	ds_write_b32 v150, v57 offset:272
	v_mul_f32_e32 v57, v148, v148
	v_pk_mul_f32 v[64:65], v[64:65], v[68:69]
	ds_write_b32 v73, v57 offset:544
	v_mul_f32_e32 v57, v131, v64
	v_pk_mov_b32 v[62:63], v[62:63], v[58:59] op_sel:[1,0]
	v_mul_f32_e32 v57, v72, v57
	v_mul_f32_e32 v147, v71, v69
	v_pk_add_f32 v[62:63], v[62:63], v[58:59] neg_lo:[0,1] neg_hi:[0,1]
	ds_write_b32 v150, v57 offset:544
	v_mul_f32_e32 v57, v147, v147
	v_pk_fma_f32 v[68:69], v[62:63], v[42:43], v[58:59] op_sel_hi:[1,0,1]
	v_mov_b32_e32 v62, v49
	v_mov_b32_e32 v63, v44
	ds_write_b32 v73, v57 offset:816
	v_mul_f32_e32 v57, v130, v65
	v_pk_add_f32 v[62:63], v[62:63], -1.0 op_sel_hi:[1,0]
	v_mul_f32_e32 v57, v72, v57
	v_mul_f32_e32 v146, v71, v68
	v_pk_fma_f32 v[62:63], v[62:63], v[0:1], 1.0 op_sel_hi:[1,0,0]
	ds_write_b32 v150, v57 offset:816
	v_mul_f32_e32 v57, v146, v146
	v_pk_mul_f32 v[62:63], v[62:63], v[68:69]
	ds_write_b32 v73, v57 offset:1088
	v_mul_f32_e32 v57, v128, v62
	v_mul_f32_e32 v57, v72, v57
	v_mul_f32_e32 v144, v71, v69
	ds_write_b32 v150, v57 offset:1088
	v_mul_f32_e32 v57, v144, v144
	v_pk_mov_b32 v[58:59], v[58:59], v[60:61] op_sel:[1,0]
	ds_write_b32 v73, v57 offset:1360
	v_mul_f32_e32 v57, v127, v63
	v_pk_add_f32 v[58:59], v[58:59], v[60:61] neg_lo:[0,1] neg_hi:[0,1]
	v_mul_f32_e32 v57, v72, v57
	v_pk_fma_f32 v[60:61], v[58:59], v[42:43], v[60:61] op_sel_hi:[1,0,1]
	ds_write_b32 v150, v57 offset:1360
	v_mul_f32_e32 v57, v71, v60
	v_mul_f32_e32 v42, v57, v57
	ds_write_b32 v73, v42 offset:1632
	v_mov_b32_e32 v42, v45
	v_pk_add_f32 v[58:59], v[42:43], -1.0 op_sel_hi:[1,0]
	v_mul_f32_e32 v42, v71, v61
	v_pk_fma_f32 v[58:59], v[58:59], v[0:1], 1.0 op_sel_hi:[1,0,0]
	s_nop 0
	v_pk_mul_f32 v[58:59], v[58:59], v[60:61]
	s_nop 0
	v_mul_f32_e32 v0, v126, v58
	v_mul_f32_e32 v0, v72, v0
	ds_write_b32 v150, v0 offset:1632
	v_mul_f32_e32 v0, v42, v42
	ds_write_b32 v73, v0 offset:1904
	v_mul_f32_e32 v0, v125, v59
	v_mul_f32_e32 v0, v72, v0
	ds_write_b32 v150, v0 offset:1904
	v_ashrrev_i32_e32 v150, 3, v135
	v_add_u32_e32 v152, s49, v150
	v_mul_lo_u32 v150, v152, s76
	s_waitcnt lgkmcnt(0)
	s_barrier
; #define LAS __attribute__((address_space(3)))
; __device__ __forceinline__ float sum8(float v) { v += dppf<0xB1>(v); v += dppf<0x4E>(v); v += dppf<0x141>(v); return v; }
; __device__ __forceinline__ void phase_scan1(Frame& F, int l) {
;     ...
;         float offs = 0.f, tot = 0.f;
; #pragma unroll
;         for (int g = 0; g < 8; ++g) { const float x = GT[g * 64 + lane]; const float sel = (g < w) ? 1.f : 0.f; tot += x; offs = fmaf(x, sel, offs); }
;         float t1, t2;
;         { const LAS float* S1 = STW + (8 * w + (lane >> 3)) * XP + 8 * (lane & 7); const LAS float* S2 = STA + (8 * w + (lane >> 3)) * XP + 8 * (lane & 7);
;           const f32x4 a0 = *(const LAS f32x4*)S1, a1 = *(const LAS f32x4*)(S1 + 4), b0 = *(const LAS f32x4*)S2, b1 = *(const LAS f32x4*)(S2 + 4);
;           t1 = sum8(((a0[0] + a0[1]) + (a0[2] + a0[3])) + ((a1[0] + a1[1]) + (a1[2] + a1[3]))); t2 = sum8(((b0[0] + b0[1]) + (b0[2] + b0[3])) + ((b1[0] + b1[1]) + (b1[2] + b1[3]))); }
;         if ((lane & 7) == 0) BON[(size_t)(m0 + 8 * w + (lane >> 3)) * NH + h] = t2;
	v_add_u32_e32 v0, v97, v70
	v_add3_u32 v153, v96, v150, v151
	ds_read2st64_b32 v[72:73], v0 offset0:17 offset1:18
	ds_read2st64_b32 v[70:71], v0 offset0:19 offset1:20
	ds_read2st64_b32 v[68:69], v0 offset0:21 offset1:22
	ds_read2st64_b32 v[60:61], v0 offset0:23 offset1:24
	v_add3_u32 v150, v91, v150, v151
	ds_read_b128 v[154:157], v153
	ds_read_b128 v[158:161], v153 offset:16
	ds_read_b128 v[162:165], v150
	ds_read_b128 v[166:169], v150 offset:16
	s_waitcnt lgkmcnt(3)
	v_add_f32_e32 v150, v154, v155
	v_add_f32_e32 v151, v156, v157
	v_add_f32_e32 v150, v150, v151
	s_waitcnt lgkmcnt(2)
	v_add_f32_e32 v151, v158, v159
	v_add_f32_e32 v153, v160, v161
	v_add_f32_e32 v151, v151, v153
	s_waitcnt lgkmcnt(1)
	v_add_f32_e32 v153, v162, v163
	v_add_f32_e32 v154, v164, v165
	v_add_f32_e32 v153, v153, v154
	s_waitcnt lgkmcnt(0)
	v_add_f32_e32 v154, v166, v167
	v_add_f32_e32 v155, v168, v169
	v_add_f32_e32 v154, v154, v155
	v_add_f32_e32 v150, v150, v151
	v_add_f32_e32 v153, v153, v154
	s_nop 0
	v_add_f32_dpp v150, v150, v150 quad_perm:[1,0,3,2] row_mask:0xf bank_mask:0xf bound_ctrl:1
	v_add_f32_dpp v153, v153, v153 quad_perm:[1,0,3,2] row_mask:0xf bank_mask:0xf bound_ctrl:1
	s_nop 0
	v_add_f32_dpp v150, v150, v150 quad_perm:[2,3,0,1] row_mask:0xf bank_mask:0xf bound_ctrl:1
	v_add_f32_dpp v153, v153, v153 quad_perm:[2,3,0,1] row_mask:0xf bank_mask:0xf bound_ctrl:1
	s_nop 0
	v_mov_b32_dpp v151, v150 row_half_mirror row_mask:0xf bank_mask:0xf bound_ctrl:1
	v_mov_b32_dpp v154, v153 row_half_mirror row_mask:0xf bank_mask:0xf bound_ctrl:1
	s_and_saveexec_b64 s[6:7], vcc
	s_cbranch_execz .LBB0_517
	v_add_u32_e32 v156, s73, v152
	v_ashrrev_i32_e32 v157, 31, v156
	v_lshlrev_b64 v[156:157], 6, v[156:157]
	v_lshl_add_u64 v[156:157], s[14:15], 0, v[156:157]
	s_lshl_b32 s92, s1, 2
	v_lshl_add_u64 v[156:157], v[156:157], 0, s[92:93]
	v_add_f32_e32 v152, v153, v154
	global_store_dword v[156:157], v152, off

; __device__ __forceinline__ void phase_scan1(Frame& F, int l) {
;     ...
;         const unsigned vo4 = (unsigned)lane * 4u; const float kkc = ldg_f32(k_k + h * 64, vo4), kac = ldg_f32(k_a + h * 64, vo4), rkc = ldg_f32(r_k + h * 64, vo4), mur = ldg_f32(mu_ + h * 64, vo4), muk = ldg_f32(mu_ + 1024 + h * 64, vo4); (void)col;
.LBB0_532:
	s_lshr_b32 s98, s72, 6
	s_cmpk_gt_i32 s72, 0xfff
	s_cselect_b32 s98, s72, s98
	s_and_b32 s98, s98, 15
	s_lshl_b32 s98, s98, 8
	v_lshlrev_b32_e32 v203, 2, v85
	s_add_u32 s100, s35, s98
	s_addc_u32 s101, s36, 0
	global_load_dword v198, v203, s[100:101]
	s_add_u32 s100, s37, s98
	s_addc_u32 s101, s38, 0
	global_load_dword v199, v203, s[100:101]
	s_add_u32 s100, s39, s98
	s_addc_u32 s101, s48, 0
	global_load_dword v200, v203, s[100:101]
	s_add_u32 s100, s52, s98
	s_addc_u32 s101, s53, 0
	global_load_dword v201, v203, s[100:101]
	s_add_u32 s100, s61, s98
	s_addc_u32 s101, s62, 0
	global_load_dword v202, v203, s[100:101]
	s_mul_hi_i32 s12, s56, 0x1800
	s_mulk_i32 s56, 0x1800
	s_add_u32 s13, s25, s56
	s_addc_u32 s12, s26, s12
	s_add_u32 s13, s13, s63
	s_addc_u32 s18, s12, 0
	s_add_u32 s12, s13, 0x1000
	s_addc_u32 s13, s18, 0
	v_lshl_add_u64 v[42:43], s[8:9], 0, v[0:1]
	v_lshl_add_u64 v[44:45], s[12:13], 0, v[0:1]
	v_add_u32_e32 v47, 0x1800, v0
	v_add_u32_e32 v46, 0x5200, v0
	v_add_u32_e32 v48, 0xa400, v0
	global_load_ushort v109, v[42:43], off
	global_load_ushort v78, v[42:43], off offset:2048
	global_load_ushort v83, v[42:43], off offset:2048
	global_load_ushort v110, v[44:45], off
	global_load_ushort v111, v46, s[8:9]
	global_load_ushort v75, v46, s[8:9] offset:2048
	global_load_ushort v112, v47, s[12:13]
	global_load_ushort v113, v48, s[8:9]
	global_load_ushort v80, v48, s[8:9] offset:2048
	v_add_u32_e32 v42, 0x3000, v0
	v_add_u32_e32 v43, 0xf600, v0
	v_add_u32_e32 v44, 0x4800, v0
	v_add_u32_e32 v45, 0x14800, v0
	v_add_u32_e32 v47, 0x19a00, v0
	v_add_u32_e32 v46, 0x6000, v0
	global_load_ushort v114, v42, s[12:13]
	global_load_ushort v115, v43, s[8:9]
	global_load_ushort v77, v43, s[8:9] offset:2048
	global_load_ushort v116, v44, s[12:13]
	global_load_ushort v117, v45, s[8:9]
	global_load_ushort v82, v45, s[8:9] offset:2048
	global_load_ushort v118, v46, s[12:13]
	global_load_ushort v119, v47, s[8:9]
	v_add_u32_e32 v42, 0x7800, v0
	v_add_u32_e32 v43, 0x1ec00, v0
	v_add_u32_e32 v44, 0x9000, v0
	v_add_u32_e32 v45, 0x23e00, v0
	v_add_u32_e32 v0, 0xa800, v0
	global_load_ushort v79, v47, s[8:9] offset:2048
	global_load_ushort v120, v42, s[12:13]
	global_load_ushort v121, v43, s[8:9]
	global_load_ushort v84, v43, s[8:9] offset:2048
	global_load_ushort v122, v44, s[12:13]
	global_load_ushort v123, v45, s[8:9]
	global_load_ushort v81, v45, s[8:9] offset:2048
	global_load_ushort v124, v0, s[12:13]

; __device__ __forceinline__ bool xb_t0(int wave) { return wave == 0 && lane_id_asm() == 0; }
; #define SEAM(k) do { if (IN(k) && IN((k) + 1)) xcd_barrier(bar); } while (0)
; __device__ __forceinline__ void xcd_barrier(const XcdBarrier& b) {
;     asm volatile("s_waitcnt vmcnt(0)" ::: "memory");
;     __syncthreads();
;     if (xb_t0(b.wave)) {
;         unsigned* bar = b.bar; unsigned bx = b.x;
;         asm volatile("" : "+s"(bar), "+s"(bx));
;         __builtin_amdgcn_s_waitcnt(0);
;         unsigned nloc = b.st[0], nx = b.st[1];
;         if (nloc == 0u) { xcd_barrier_complete(bar, bx, nloc, nx); b.st[0] = nloc; b.st[1] = nx; }
; __global__ void __launch_bounds__(NWAVES * 64, 2) trunk_fwd(Args args) {
;     ...
;         SEAM(s0 + 3);
.LBB0_580:
	v_mov_b64_e32 v[198:199], 0x27f
	v_mov_b64_e32 v[200:201], 0x200
	v_mov_b64_e32 v[202:203], 0x2ff
	s_add_i32 s0, s61, 5
	s_cmp_ge_i32 s0, s51
	s_cbranch_scc1 .LBB0_628
	s_waitcnt vmcnt(0)
	v_cmp_ne_u32_e32 vcc, 1, v238
	s_waitcnt lgkmcnt(0)
	s_barrier
	s_cbranch_vccnz .LBB0_627
	s_waitcnt vmcnt(0)
	v_mbcnt_lo_u32_b32 v0, -1, 0
	v_mbcnt_hi_u32_b32 v0, -1, v0
	s_nop 0
	v_cmp_eq_u32_e32 vcc, 0, v0
	s_and_saveexec_b64 s[38:39], vcc
	s_cbranch_execz .LBB0_626
	v_readlane_b32 s52, v254, 8
	v_readlane_b32 s6, v254, 11
	v_readlane_b32 s53, v254, 9
	v_readlane_b32 s1, v254, 10
	v_mov_b32_e32 v0, s6
	s_waitcnt vmcnt(0) expcnt(0) lgkmcnt(0)
	ds_read_b32 v2, v0
	ds_read_b32 v0, v0 offset:4
	s_waitcnt lgkmcnt(1)
	v_cmp_ne_u32_e32 vcc, 0, v2
	s_cbranch_vccnz .LBB0_597
	v_readlane_b32 s6, v254, 2
	v_readlane_b32 s7, v254, 3
	s_load_dwordx2 s[10:11], s[6:7], 0x4
	s_add_u32 s6, s52, 0x1000
	s_addc_u32 s7, s53, 0
	s_add_u32 s8, s52, 0x1100
	s_addc_u32 s9, s53, 0
	s_waitcnt lgkmcnt(0)
	s_mul_i32 s34, s10, s33
	s_add_u32 s10, s52, 0x1200
	s_mul_i32 s34, s34, s11
	s_addc_u32 s11, s53, 0
	s_add_u32 s12, s52, 0x1300
	s_addc_u32 s13, s53, 0
	s_mov_b32 s35, 1
	s_mov_b64 s[14:15], 0
	s_branch .LBB0_587
